# A/B of the static priority raise: fast attention units without s_setprio 1 for waves 4-7 (priority lever, per-half test)
# speedup vs baseline: 1.0118x; 1.0118x over previous
; __device__ __forceinline__ int v_rd_base(int lane) { return ((lane & 3) << 3) | (((lane >> 2) & 3) << 6) | (((lane >> 4) & 1) << 5) | (((lane >> 5) & 1) << 8); }
; #define DMA_K(t, buf) do { const char* kb_ = (const char*)Kh + (size_t)(t) * TILEB; \
;         glds16(kb_ + ksrc[0], (unsigned)__builtin_amdgcn_readfirstlane(lds0 + OFF_K + (buf) * SHM_K + (DQK == 128 ? widu * 2048 : widu * 1024))); \
;         if (DQK == 128) glds16(kb_ + ksrc[1], (unsigned)__builtin_amdgcn_readfirstlane(lds0 + OFF_K + (buf) * SHM_K + widu * 2048 + 1024)); } while (0)
; #define WBAR0() do { asm volatile("s_waitcnt vmcnt(0)" ::: "memory"); __syncthreads(); } while (0)
;     ...
;     char* qs = lds + OFF_Q + wid * (2 * 1024) + lane * 16;
;     {
;         const bf16_t* Qw = Qb + (size_t)(wid * QBLK + r32) * LDQ + hi * 8;
; #pragma unroll
;         for (int d0 = 0; d0 < NREG; ++d0) qr[d0] = *(const bf16x8*)(Qw + d0 * 16);
; #pragma unroll
;         for (int d0 = NREG; d0 < ND0; ++d0) *(bf16x8*)(qs + (d0 - NREG) * 1024) = *(const bf16x8*)(Qw + d0 * 16);
;     }
;     const int widu = __builtin_amdgcn_readfirstlane(wid);
;     const int vb0 = (int)(uintptr_t)V_lds + v_rd_base(lane);
;     unsigned ksrc[2], vsrc[2];
; #pragma unroll
;     for (int i = 0; i < 2; ++i) {
;         if (DQK == 128) { const int j = wid * 2 + i, row = 4 * j + (lane >> 4), c = (lane & 15) ^ (row & 15); ksrc[i] = (unsigned)(row * LDK + c * 8) * 2u; }
;         else { const int row = 8 * wid + (lane >> 3), c = (lane & 7) ^ ((row >> 1) & 7); ksrc[i] = (unsigned)(row * LDK + c * 8) * 2u; }
;         const int j = wid * 2 + i, st = 2 * j + (lane >> 5), kk = (st >> 2) * 8 + ((lane & 31) >> 2), c = (st & 3) * 32 + (lane & 3) * 8;
;         const int k = (kk & ~0xC) | ((kk & 4) << 1) | ((kk & 8) >> 1);
;         vsrc[i] = (unsigned)(k * LDK + c) * 2u;
;     }
;     constexpr size_t TILEB = (size_t)KVBLK * LDK * 2;
;     const unsigned lds0 = (unsigned)(uintptr_t)lds;
;     ...
;     f32x16 pA0, pA1, pB0, pB1; bf16x8 pa0, pa1, pa2, pa3;
;     DMA_K(0, 0); WBAR0();
;     if (__builtin_amdgcn_readfirstlane(tid_) >= 256) __builtin_amdgcn_s_setprio(1);
.LBB0_526:
	s_ashr_i32 s45, s51, 8
	s_lshl_b32 s1, s51, 8
	s_lshl_b32 s0, s45, 12
	s_and_b32 s1, s1, 0xf00
	s_or_b32 s0, s0, s1
	s_bfe_u32 s52, s51, 0x20006
	s_mul_hi_i32 s1, s0, 0x3800
	s_mulk_i32 s0, 0x3800
	s_add_u32 s0, s12, s0
	s_addc_u32 s1, s13, s1
	s_lshl_b32 s42, s51, 4
	s_and_b32 s42, s42, 0x300
	s_lshl_b32 s43, s52, 10
	s_or_b32 s42, s43, s42
	s_add_u32 s42, s0, s42
	v_mov_b32_e32 v2, v218
	s_addc_u32 s43, s1, 0
	v_mov_b64_e32 v[4:5], s[42:43]
	v_ashrrev_i32_e32 v14, 6, v2
	v_and_b32_e32 v0, 31, v2
	v_bfe_u32 v1, v2, 5, 1
	v_lshl_or_b32 v3, v14, 5, v0
	v_mad_i64_i32 v[4:5], s[0:1], v3, s33, v[4:5]
	v_lshlrev_b32_e32 v16, 4, v1
	v_mov_b32_e32 v17, v161
	v_lshl_add_u64 v[4:5], v[4:5], 0, v[16:17]
	global_load_dwordx4 v[6:9], v[4:5], off offset:192
	global_load_dwordx4 v[10:13], v[4:5], off offset:224
	global_load_dwordx4 v[116:119], v[4:5], off
	global_load_dwordx4 v[112:115], v[4:5], off offset:32
	global_load_dwordx4 v[108:111], v[4:5], off offset:64
	global_load_dwordx4 v[104:107], v[4:5], off offset:96
	global_load_dwordx4 v[100:103], v[4:5], off offset:128
	global_load_dwordx4 v[96:99], v[4:5], off offset:160
	v_and_b32_e32 v4, 63, v2
	v_bfe_u32 v15, v2, 4, 2
	v_lshlrev_b32_e32 v3, 3, v14
	s_movk_i32 s0, 0xc00
	s_mul_hi_i32 s44, s45, 0x1980000
	s_mul_i32 s45, s45, 0x1980000
	v_lshlrev_b32_e32 v5, 4, v4
	v_lshl_add_u32 v17, v14, 11, s34
	v_readfirstlane_b32 s53, v14
	v_or_b32_e32 v14, v3, v15
	v_add_u32_e32 v229, v17, v5
	v_mul_lo_u32 v17, v14, s0
	s_add_u32 s0, s10, s45
	s_addc_u32 s1, s11, s44
	s_lshl_b32 s52, s52, 8
	s_add_u32 s0, s0, s52
	v_bitop3_b32 v15, v3, v2, v15 bitop3:0x36
	s_addc_u32 s1, s1, 0
	s_lshl_b32 s52, s53, 11
	v_lshlrev_b32_e32 v15, 3, v15
	v_bitop3_b32 v14, v14, v2, 4 bitop3:0x36
	s_cmp_lg_u32 0, -1
	v_and_or_b32 v15, v15, s35, v17
	v_lshlrev_b32_e32 v14, 3, v14
	s_cselect_b32 s53, 0, 0
	v_lshlrev_b32_e32 v160, 1, v15
	v_and_or_b32 v14, v14, s35, v17
	s_add_i32 s54, s53, s52
	v_mov_b32_e32 v163, v161
	v_lshl_add_u32 v162, v14, 1, v226
	v_lshl_add_u64 v[14:15], s[0:1], 0, v[160:161]
	s_add_i32 s53, s54, 0x8000
	v_lshl_add_u64 v[18:19], s[0:1], 0, v[162:163]
	s_add_i32 s54, s54, 0x8400
	s_waitcnt vmcnt(7)
	ds_write_b128 v229, v[6:9]
	s_waitcnt vmcnt(6)
	ds_write_b128 v229, v[10:13] offset:1024
	s_mov_b32 s55, m0
	s_mov_b32 m0, s53
	s_nop 0
	global_load_lds_dwordx4 v[14:15], off
	s_mov_b32 m0, s55
	s_nop 0
	s_mov_b32 s55, m0
	s_mov_b32 m0, s54
	s_nop 0
	global_load_lds_dwordx4 v[18:19], off
	s_mov_b32 m0, s55
	s_waitcnt vmcnt(0)
	s_waitcnt lgkmcnt(0)
	v_readfirstlane_b32 s55, v2
	s_cmpk_lt_i32 s55, 0x100
	s_barrier
	s_cbranch_scc1 .LBB0_528
	s_setprio 0

; __device__ __forceinline__ int v_rd_base(int lane) { return ((lane & 3) << 3) | (((lane >> 2) & 3) << 6) | (((lane >> 4) & 1) << 5) | (((lane >> 5) & 1) << 8); }
; #define DMA_K(t, buf) do { const char* kb_ = (const char*)Kh + (size_t)(t) * TILEB; \
;         glds16(kb_ + ksrc[0], (unsigned)__builtin_amdgcn_readfirstlane(lds0 + OFF_K + (buf) * SHM_K + (DQK == 128 ? widu * 2048 : widu * 1024))); \
;         if (DQK == 128) glds16(kb_ + ksrc[1], (unsigned)__builtin_amdgcn_readfirstlane(lds0 + OFF_K + (buf) * SHM_K + widu * 2048 + 1024)); } while (0)
; #define WBAR0() do { asm volatile("s_waitcnt vmcnt(0)" ::: "memory"); __syncthreads(); } while (0)
;     ...
;         const bf16_t* Qw = Qb + (size_t)(wid * QBLK + r32) * LDQ + hi * 8;
; #pragma unroll
;         for (int d0 = 0; d0 < NREG; ++d0) qr[d0] = *(const bf16x8*)(Qw + d0 * 16);
; #pragma unroll
;         for (int d0 = NREG; d0 < ND0; ++d0) *(bf16x8*)(qs + (d0 - NREG) * 1024) = *(const bf16x8*)(Qw + d0 * 16);
;     }
;     const int widu = __builtin_amdgcn_readfirstlane(wid);
;     const int vb0 = (int)(uintptr_t)V_lds + v_rd_base(lane);
;     unsigned ksrc[2], vsrc[2];
; #pragma unroll
;     for (int i = 0; i < 2; ++i) {
;         if (DQK == 128) { const int j = wid * 2 + i, row = 4 * j + (lane >> 4), c = (lane & 15) ^ (row & 15); ksrc[i] = (unsigned)(row * LDK + c * 8) * 2u; }
;         else { const int row = 8 * wid + (lane >> 3), c = (lane & 7) ^ ((row >> 1) & 7); ksrc[i] = (unsigned)(row * LDK + c * 8) * 2u; }
;         const int j = wid * 2 + i, st = 2 * j + (lane >> 5), kk = (st >> 2) * 8 + ((lane & 31) >> 2), c = (st & 3) * 32 + (lane & 3) * 8;
;         const int k = (kk & ~0xC) | ((kk & 4) << 1) | ((kk & 8) >> 1);
;         vsrc[i] = (unsigned)(k * LDK + c) * 2u;
;     }
;     constexpr size_t TILEB = (size_t)KVBLK * LDK * 2;
;     const unsigned lds0 = (unsigned)(uintptr_t)lds;
;     ...
;     f32x16 pA0, pA1, pB0, pB1; bf16x8 pa0, pa1, pa2, pa3;
;     DMA_K(0, 0); WBAR0();
;     if (__builtin_amdgcn_readfirstlane(tid_) >= 256) __builtin_amdgcn_s_setprio(1);
.LBB0_558:
	s_ashr_i32 s0, s54, 7
	s_lshl_b32 s4, s54, 8
	s_lshl_b32 s1, s0, 12
	s_and_b32 s4, s4, 0xf00
	s_or_b32 s1, s1, s4
	s_mul_hi_i32 s4, s1, 0x3800
	s_mulk_i32 s1, 0x3800
	s_add_u32 s1, s12, s1
	s_addc_u32 s4, s13, s4
	s_lshl_b32 s5, s54, 3
	s_and_b32 s5, s5, 0x380
	s_lshl_b32 s48, s5, 1
	s_add_u32 s1, s1, s48
	s_addc_u32 s5, s4, 0
	s_add_u32 s4, s1, 0x1000
	s_addc_u32 s5, s5, 0
	v_lshl_add_u64 v[0:1], v[130:131], 1, s[4:5]
	v_lshl_add_u64 v[144:145], v[0:1], 0, v[138:139]
	global_load_dwordx4 v[108:111], v[144:145], off
	global_load_dwordx4 v[104:107], v[144:145], off offset:32
	global_load_dwordx4 v[100:103], v[144:145], off offset:64
	global_load_dwordx4 v[96:99], v[144:145], off offset:96
	s_mul_i32 s47, s0, 0x1980000
	s_mul_hi_i32 s46, s0, 0x1980000
	s_add_u32 s72, s10, s47
	s_addc_u32 s74, s11, s46
	s_add_u32 s0, s72, s48
	s_addc_u32 s1, s74, 0
	s_add_u32 s76, s0, 0x800
	v_readfirstlane_b32 s49, v202
	s_addc_u32 s77, s1, 0
	s_lshl_b32 s73, s49, 10
	s_cmp_lg_u32 0, -1
	s_cselect_b32 s55, 0, 0
	s_add_i32 s55, s55, s73
	v_lshl_add_u64 v[142:143], s[76:77], 0, v[136:137]
	s_add_i32 s55, s55, 0x8000
	s_mov_b32 s75, m0
	s_mov_b32 m0, s55
	s_nop 0
	global_load_lds_dwordx4 v[142:143], off
	s_mov_b32 m0, s75
	s_waitcnt vmcnt(0)
	s_nop 0
	v_readfirstlane_b32 s75, v218
	s_cmpk_lt_i32 s75, 0x100
	s_barrier
	s_cbranch_scc1 .LBB0_560
	s_setprio 0

; #define SBAR() __builtin_amdgcn_sched_barrier(0)
; #define DMA_K(t, buf) do { const char* kb_ = (const char*)Kh + (size_t)(t) * TILEB; \
;         glds16(kb_ + ksrc[0], (unsigned)__builtin_amdgcn_readfirstlane(lds0 + OFF_K + (buf) * SHM_K + (DQK == 128 ? widu * 2048 : widu * 1024))); \
;         if (DQK == 128) glds16(kb_ + ksrc[1], (unsigned)__builtin_amdgcn_readfirstlane(lds0 + OFF_K + (buf) * SHM_K + widu * 2048 + 1024)); } while (0)
; #define DMA_V(t, buf) do { const char* vb_ = (const char*)Vh + (size_t)(t) * TILEB; \
;         glds16(vb_ + vsrc[0], (unsigned)__builtin_amdgcn_readfirstlane(lds0 + (buf) * SHM_V + widu * 2048)); \
;         glds16(vb_ + vsrc[1], (unsigned)__builtin_amdgcn_readfirstlane(lds0 + (buf) * SHM_V + widu * 2048 + 1024)); } while (0)
; #define WBAR0() do { asm volatile("s_waitcnt vmcnt(0)" ::: "memory"); __syncthreads(); } while (0)
; #define EXPH(P) do { _Pragma("unroll") for (int r = 0; r < 16; ++r) P[r] = __builtin_amdgcn_exp2f(P[r]); } while (0)
;     ...
;     for (int k = 1; k + 1 < NT; k += 2) {
;         DMA_K(k + 1, 0); DMA_V(k, 1); SBAR();
;         if (isY) { EXPH(pA0); }
;         SBAR(); qkt_mix<DQK, NREG>(pB0, pB1, K_lds + SHM_K, qr, qs, r32, hi);
;         finishSM<true>(pA0, pA1, dummy_a, l_reg, pa0, pa1, pa2, pa3); SBAR();
;         pv_d0(o, vb0, pa0, pa1, pa2, pa3);
;         if (!isY) { EXPH(pB0); }
;         WBAR0();
.LBB0_561:
	v_lshl_add_u64 v[80:81], v[152:153], 0, s[22:23]
	s_mov_b32 s0, m0
	s_mov_b32 m0, s55
	s_nop 0
	global_load_lds_dwordx4 v[80:81], off
	s_mov_b32 m0, s0
	s_cmp_lg_u32 0, -1
	s_cselect_b32 s0, 0, 0
	s_add_i32 s0, s0, s73
	v_lshl_add_u64 v[186:187], s[48:49], 0, v[132:133]
	s_add_i32 s1, s0, 0x4000
	s_mov_b32 s77, m0
	s_mov_b32 m0, s1
	s_nop 0
	global_load_lds_dwordx4 v[186:187], off
	s_mov_b32 m0, s77
	v_lshl_add_u64 v[80:81], v[186:187], 0, s[20:21]
	s_addk_i32 s0, 0x4400
	s_mov_b32 s1, m0
	s_mov_b32 m0, s0
	s_nop 0
	global_load_lds_dwordx4 v[80:81], off
	s_mov_b32 m0, s1
	ds_read_b128 v[80:83], v205 offset:40960
	ds_read_b128 v[124:127], v205 offset:45056
	ds_read_b128 v[112:115], v206 offset:40960
	ds_read_b128 v[120:123], v206 offset:45056
	s_waitcnt lgkmcnt(3)
	v_mfma_f32_32x32x16_bf16 v[80:95], v[80:83], v[108:111], 0
	s_waitcnt lgkmcnt(1)
	v_mfma_f32_32x32x16_bf16 v[80:95], v[112:115], v[104:107], v[80:95]
	ds_read_b128 v[112:115], v207 offset:40960
	ds_read_b128 v[116:119], v207 offset:45056
	s_waitcnt lgkmcnt(1)
	v_mfma_f32_32x32x16_bf16 v[80:95], v[112:115], v[100:103], v[80:95]
	ds_read_b128 v[172:175], v208 offset:40960
	ds_read_b128 v[112:115], v208 offset:45056
	s_waitcnt lgkmcnt(1)
	v_mfma_f32_32x32x16_bf16 v[80:95], v[172:175], v[96:99], v[80:95]
	v_exp_f32_e32 v199, v64
	v_exp_f32_e32 v197, v65
	v_exp_f32_e32 v198, v66
	v_exp_f32_e32 v196, v67
	v_exp_f32_e32 v67, v69
	v_exp_f32_e32 v66, v71
	v_exp_f32_e32 v65, v72
	v_exp_f32_e32 v64, v74
	v_exp_f32_e32 v195, v68
	v_exp_f32_e32 v194, v70
	v_exp_f32_e32 v193, v73
	v_exp_f32_e32 v192, v75
	v_exp_f32_e32 v191, v76
	v_exp_f32_e32 v189, v77
	v_exp_f32_e32 v190, v78
	v_exp_f32_e32 v188, v79
	v_cvt_pk_bf16_f32 v68, v171, v169
	v_cvt_pk_bf16_f32 v69, v170, v168
	v_cvt_pk_bf16_f32 v70, v167, v165
	v_cvt_pk_bf16_f32 v71, v166, v164
	v_cvt_pk_bf16_f32 v72, v163, v161
	v_cvt_pk_bf16_f32 v73, v162, v160
	v_cvt_pk_bf16_f32 v74, v159, v157
	v_cvt_pk_bf16_f32 v75, v158, v156
	v_cvt_pk_bf16_f32 v76, v199, v197
	v_cvt_pk_bf16_f32 v77, v198, v196
	v_cvt_pk_bf16_f32 v78, v195, v67
	v_cvt_pk_bf16_f32 v79, v194, v66
	s_nop 0
	v_permlane32_swap_b32_e32 v68, v70
	v_permlane32_swap_b32_e32 v69, v71
	v_permlane32_swap_b32_e32 v72, v74
	v_permlane32_swap_b32_e32 v73, v75
	v_permlane32_swap_b32_e32 v76, v78
	v_permlane32_swap_b32_e32 v77, v79
	v_cvt_pk_bf16_f32 v210, v65, v193
	v_cvt_pk_bf16_f32 v211, v64, v192
	v_cvt_pk_bf16_f32 v212, v191, v189
	v_cvt_pk_bf16_f32 v213, v190, v188
	s_nop 0
	v_permlane32_swap_b32_e32 v210, v212
	v_permlane32_swap_b32_e32 v211, v213
	ds_read_b64_tr_b16 v[172:173], v203 offset:0
	ds_read_b64_tr_b16 v[174:175], v203 offset:0x800
	ds_read_b64_tr_b16 v[176:177], v203 offset:0x1000
	ds_read_b64_tr_b16 v[178:179], v203 offset:0x1800
	ds_read_b64_tr_b16 v[180:181], v203 offset:0x2000
	ds_read_b64_tr_b16 v[182:183], v203 offset:0x2800
	ds_read_b64_tr_b16 v[214:215], v203 offset:0x3000
	ds_read_b64_tr_b16 v[216:217], v203 offset:0x3800
	s_waitcnt lgkmcnt(0)
	s_nop 0
	v_mfma_f32_32x32x16_bf16 v[0:15], v[68:71], v[172:175], v[0:15]
	ds_read_b64_tr_b16 v[172:173], v203 offset:0x200
	ds_read_b64_tr_b16 v[174:175], v203 offset:0xa00
	v_mfma_f32_32x32x16_bf16 v[0:15], v[72:75], v[176:179], v[0:15]
	ds_read_b64_tr_b16 v[176:177], v203 offset:0x1200
	ds_read_b64_tr_b16 v[178:179], v203 offset:0x1a00
	v_mfma_f32_32x32x16_bf16 v[0:15], v[76:79], v[180:183], v[0:15]
	ds_read_b64_tr_b16 v[180:181], v203 offset:0x2200
	ds_read_b64_tr_b16 v[182:183], v203 offset:0x2a00
	ds_read_b64_tr_b16 v[224:225], v203 offset:0x3200
	ds_read_b64_tr_b16 v[226:227], v203 offset:0x3a00
	s_waitcnt lgkmcnt(0)
	v_mfma_f32_32x32x16_bf16 v[0:15], v[210:213], v[214:217], v[0:15]
	v_mfma_f32_32x32x16_bf16 v[16:31], v[68:71], v[172:175], v[16:31]
	ds_read_b64_tr_b16 v[172:173], v203 offset:0x400
	ds_read_b64_tr_b16 v[174:175], v203 offset:0xc00
	v_mfma_f32_32x32x16_bf16 v[16:31], v[72:75], v[176:179], v[16:31]
	ds_read_b64_tr_b16 v[176:177], v203 offset:0x1400
	ds_read_b64_tr_b16 v[178:179], v203 offset:0x1c00
	v_mfma_f32_32x32x16_bf16 v[16:31], v[76:79], v[180:183], v[16:31]
	ds_read_b64_tr_b16 v[180:181], v203 offset:0x2400
	ds_read_b64_tr_b16 v[182:183], v203 offset:0x2c00
	ds_read_b64_tr_b16 v[214:215], v203 offset:0x3400
	ds_read_b64_tr_b16 v[216:217], v203 offset:0x3c00
	s_waitcnt lgkmcnt(0)
	v_mfma_f32_32x32x16_bf16 v[16:31], v[210:213], v[224:227], v[16:31]
	v_mfma_f32_32x32x16_bf16 v[32:47], v[68:71], v[172:175], v[32:47]
	ds_read_b64_tr_b16 v[172:173], v203 offset:0x600
	ds_read_b64_tr_b16 v[174:175], v203 offset:0xe00
	v_mfma_f32_32x32x16_bf16 v[32:47], v[72:75], v[176:179], v[32:47]
	ds_read_b64_tr_b16 v[176:177], v203 offset:0x1600
	ds_read_b64_tr_b16 v[178:179], v203 offset:0x1e00
	ds_read_b64_tr_b16 v[224:225], v203 offset:0x2600
	ds_read_b64_tr_b16 v[226:227], v203 offset:0x2e00
	ds_read_b64_tr_b16 v[228:229], v203 offset:0x3600
	ds_read_b64_tr_b16 v[230:231], v203 offset:0x3e00
	s_waitcnt lgkmcnt(0)
	v_mfma_f32_32x32x16_bf16 v[32:47], v[76:79], v[180:183], v[32:47]
	v_mfma_f32_32x32x16_bf16 v[32:47], v[210:213], v[214:217], v[32:47]
	v_mfma_f32_32x32x16_bf16 v[48:63], v[68:71], v[172:175], v[48:63]
	v_exp_f32_e32 v180, v86
	v_exp_f32_e32 v175, v89
	v_exp_f32_e32 v185, v80
	v_exp_f32_e32 v183, v81
	v_exp_f32_e32 v184, v82
	v_exp_f32_e32 v182, v83
	v_add_f32_e32 v80, v170, v198
	v_add_f32_e32 v81, v171, v199
	v_mfma_f32_32x32x16_bf16 v[48:63], v[72:75], v[176:179], v[48:63]
	v_exp_f32_e32 v178, v87
	v_exp_f32_e32 v177, v88
	v_add_f32_e32 v86, v164, v66
	v_add_f32_e32 v87, v165, v67
	v_add_f32_e32 v88, v162, v64
	v_add_f32_e32 v89, v163, v65
	v_add_f32_e32 v82, v168, v196
	v_add_f32_e32 v83, v169, v197
	v_exp_f32_e32 v181, v84
	v_exp_f32_e32 v179, v85
	v_mfma_f32_32x32x16_bf16 v[48:63], v[76:79], v[224:227], v[48:63]
	v_add_f32_e64 v84, v166, v194
	v_add_f32_e64 v85, v167, v195
	v_exp_f32_e32 v176, v90
	v_exp_f32_e32 v174, v91
	v_add_f32_e32 v90, v160, v192
	v_add_f32_e32 v91, v161, v193
	v_add_f32_e32 v80, v84, v80
	v_add_f32_e32 v81, v85, v81
	v_mfma_f32_32x32x16_bf16 v[64:79], v[124:127], v[108:111], 0
	v_add_f32_e64 v82, v86, v82
	v_add_f32_e64 v83, v87, v83
	v_exp_f32_e32 v173, v92
	v_exp_f32_e32 v155, v93
	v_exp_f32_e32 v172, v94
	v_exp_f32_e32 v154, v95
	v_add_f32_e32 v92, v158, v190
	v_add_f32_e32 v93, v159, v191
	v_add_f32_e32 v94, v156, v188
	v_add_f32_e32 v95, v157, v189
	v_mfma_f32_32x32x16_bf16 v[64:79], v[120:123], v[104:107], v[64:79]
	v_add_f32_e64 v80, v88, v80
	v_add_f32_e64 v81, v89, v81
	v_add_f32_e64 v82, v90, v82
	v_add_f32_e64 v83, v91, v83
	v_add_f32_e64 v80, v92, v80
	v_add_f32_e64 v81, v93, v81
	v_add_f32_e32 v82, v94, v82
	v_add_f32_e32 v83, v95, v83
	s_waitcnt vmcnt(0)
	s_waitcnt lgkmcnt(0)
	v_add_f32_e32 v80, v82, v80
	v_add_f32_e32 v81, v83, v81
	v_mfma_f32_32x32x16_bf16 v[64:79], v[116:119], v[100:103], v[64:79]
	s_barrier
; #define SBAR() __builtin_amdgcn_sched_barrier(0)
; #define DMA_K(t, buf) do { const char* kb_ = (const char*)Kh + (size_t)(t) * TILEB; \
;         glds16(kb_ + ksrc[0], (unsigned)__builtin_amdgcn_readfirstlane(lds0 + OFF_K + (buf) * SHM_K + (DQK == 128 ? widu * 2048 : widu * 1024))); \
;         if (DQK == 128) glds16(kb_ + ksrc[1], (unsigned)__builtin_amdgcn_readfirstlane(lds0 + OFF_K + (buf) * SHM_K + widu * 2048 + 1024)); } while (0)
; #define DMA_V(t, buf) do { const char* vb_ = (const char*)Vh + (size_t)(t) * TILEB; \
;         glds16(vb_ + vsrc[0], (unsigned)__builtin_amdgcn_readfirstlane(lds0 + (buf) * SHM_V + widu * 2048)); \
;         glds16(vb_ + vsrc[1], (unsigned)__builtin_amdgcn_readfirstlane(lds0 + (buf) * SHM_V + widu * 2048 + 1024)); } while (0)
; #define EXPH(P) do { _Pragma("unroll") for (int r = 0; r < 16; ++r) P[r] = __builtin_amdgcn_exp2f(P[r]); } while (0)
;     ...
;         DMA_K(k + 2, 1); DMA_V(k + 1, 0); SBAR();
;         if (isY) { EXPH(pB0); }
;         SBAR(); qkt_mix<DQK, NREG>(pA0, pA1, K_lds, qr, qs, r32, hi);
;         finishSM<true>(pB0, pB1, dummy_a, l_reg, pa0, pa1, pa2, pa3); SBAR();
;         pv_d0(o, vb0 + SHM_V, pa0, pa1, pa2, pa3);
;         if (!isY) { EXPH(pA0); }
	s_mov_b32 s0, m0
	s_mov_b32 m0, s74
	s_nop 0
	global_load_lds_dwordx4 v[152:153], off
	s_mov_b32 m0, s0
	v_add_f32_e32 v141, v80, v81
	v_lshl_add_u64 v[80:81], v[186:187], 0, s[6:7]
	s_mov_b32 s0, m0
	s_mov_b32 m0, s75
	s_nop 0
	global_load_lds_dwordx4 v[80:81], off
	s_mov_b32 m0, s0
	v_lshl_add_u64 v[80:81], v[186:187], 0, s[26:27]
	v_mfma_f32_32x32x16_bf16 v[48:63], v[210:213], v[228:231], v[48:63]
	s_mov_b32 s0, m0
	s_mov_b32 m0, s76
	s_nop 0
	global_load_lds_dwordx4 v[80:81], off
	s_mov_b32 m0, s0
	v_mfma_f32_32x32x16_bf16 v[64:79], v[112:115], v[96:99], v[64:79]
	ds_read_b128 v[80:83], v205 offset:32768
	ds_read_b128 v[156:159], v205 offset:36864
	ds_read_b128 v[112:115], v206 offset:32768
	ds_read_b128 v[124:127], v206 offset:36864
	s_waitcnt lgkmcnt(3)
	v_mfma_f32_32x32x16_bf16 v[80:95], v[80:83], v[108:111], 0
	s_waitcnt lgkmcnt(1)
	v_mfma_f32_32x32x16_bf16 v[80:95], v[112:115], v[104:107], v[80:95]
	ds_read_b128 v[112:115], v207 offset:32768
	ds_read_b128 v[120:123], v207 offset:36864
	s_waitcnt lgkmcnt(1)
	v_mfma_f32_32x32x16_bf16 v[80:95], v[112:115], v[100:103], v[80:95]
	ds_read_b128 v[116:119], v208 offset:32768
	ds_read_b128 v[112:115], v208 offset:36864
	s_waitcnt lgkmcnt(1)
	v_mfma_f32_32x32x16_bf16 v[80:95], v[116:119], v[96:99], v[80:95]
	v_exp_f32_e32 v201, v64
	v_exp_f32_e32 v199, v65
	v_exp_f32_e32 v200, v66
	v_exp_f32_e32 v198, v67
	v_exp_f32_e32 v197, v68
	v_exp_f32_e32 v195, v69
	v_exp_f32_e32 v196, v70
	v_exp_f32_e32 v194, v71
	v_exp_f32_e32 v193, v72
	v_exp_f32_e32 v191, v73
	v_exp_f32_e32 v192, v74
	v_exp_f32_e32 v190, v75
	v_exp_f32_e32 v189, v76
	v_exp_f32_e32 v187, v77
	v_exp_f32_e32 v188, v78
	v_exp_f32_e32 v186, v79
	v_cvt_pk_bf16_f32 v64, v185, v183
	v_cvt_pk_bf16_f32 v65, v184, v182
	v_cvt_pk_bf16_f32 v66, v181, v179
	v_cvt_pk_bf16_f32 v67, v180, v178
	v_cvt_pk_bf16_f32 v160, v177, v175
	v_cvt_pk_bf16_f32 v161, v176, v174
	v_cvt_pk_bf16_f32 v162, v173, v155
	v_cvt_pk_bf16_f32 v163, v172, v154
	s_nop 0
	v_permlane32_swap_b32_e32 v64, v66
	v_permlane32_swap_b32_e32 v65, v67
	v_permlane32_swap_b32_e32 v160, v162
	v_permlane32_swap_b32_e32 v161, v163
	v_cvt_pk_bf16_f32 v210, v201, v199
	v_cvt_pk_bf16_f32 v211, v200, v198
	v_cvt_pk_bf16_f32 v212, v197, v195
	v_cvt_pk_bf16_f32 v213, v196, v194
	v_cvt_pk_bf16_f32 v116, v193, v191
	v_cvt_pk_bf16_f32 v117, v192, v190
	v_cvt_pk_bf16_f32 v118, v189, v187
	v_cvt_pk_bf16_f32 v119, v188, v186
	s_nop 0
	v_permlane32_swap_b32_e32 v210, v212
	v_permlane32_swap_b32_e32 v211, v213
	v_permlane32_swap_b32_e32 v116, v118
	v_permlane32_swap_b32_e32 v117, v119
	ds_read_b64_tr_b16 v[68:69], v204 offset:0
	ds_read_b64_tr_b16 v[70:71], v204 offset:0x800
	ds_read_b64_tr_b16 v[72:73], v204 offset:0x1000
	ds_read_b64_tr_b16 v[74:75], v204 offset:0x1800
	ds_read_b64_tr_b16 v[76:77], v204 offset:0x2000
	ds_read_b64_tr_b16 v[78:79], v204 offset:0x2800
	ds_read_b64_tr_b16 v[164:165], v204 offset:0x3000
	ds_read_b64_tr_b16 v[166:167], v204 offset:0x3800
	s_waitcnt lgkmcnt(0)
	s_nop 0
	v_mfma_f32_32x32x16_bf16 v[0:15], v[64:67], v[68:71], v[0:15]
	ds_read_b64_tr_b16 v[68:69], v204 offset:0x200
	ds_read_b64_tr_b16 v[70:71], v204 offset:0xa00
	v_mfma_f32_32x32x16_bf16 v[0:15], v[160:163], v[72:75], v[0:15]
	ds_read_b64_tr_b16 v[72:73], v204 offset:0x1200
	ds_read_b64_tr_b16 v[74:75], v204 offset:0x1a00
	v_mfma_f32_32x32x16_bf16 v[0:15], v[210:213], v[76:79], v[0:15]
	ds_read_b64_tr_b16 v[76:77], v204 offset:0x2200
	ds_read_b64_tr_b16 v[78:79], v204 offset:0x2a00
	ds_read_b64_tr_b16 v[168:169], v204 offset:0x3200
	ds_read_b64_tr_b16 v[170:171], v204 offset:0x3a00
	s_waitcnt lgkmcnt(0)
	v_mfma_f32_32x32x16_bf16 v[0:15], v[116:119], v[164:167], v[0:15]
	v_mfma_f32_32x32x16_bf16 v[16:31], v[64:67], v[68:71], v[16:31]
	ds_read_b64_tr_b16 v[68:69], v204 offset:0x400
	ds_read_b64_tr_b16 v[70:71], v204 offset:0xc00
	v_mfma_f32_32x32x16_bf16 v[16:31], v[160:163], v[72:75], v[16:31]
	ds_read_b64_tr_b16 v[72:73], v204 offset:0x1400
	ds_read_b64_tr_b16 v[74:75], v204 offset:0x1c00
	v_mfma_f32_32x32x16_bf16 v[16:31], v[210:213], v[76:79], v[16:31]
	ds_read_b64_tr_b16 v[76:77], v204 offset:0x2400
	ds_read_b64_tr_b16 v[78:79], v204 offset:0x2c00
	ds_read_b64_tr_b16 v[164:165], v204 offset:0x3400
	ds_read_b64_tr_b16 v[166:167], v204 offset:0x3c00
	s_waitcnt lgkmcnt(0)
	v_mfma_f32_32x32x16_bf16 v[16:31], v[116:119], v[168:171], v[16:31]
	v_mfma_f32_32x32x16_bf16 v[32:47], v[64:67], v[68:71], v[32:47]
	ds_read_b64_tr_b16 v[68:69], v204 offset:0x600
	ds_read_b64_tr_b16 v[70:71], v204 offset:0xe00
	ds_read_b64_tr_b16 v[214:215], v204 offset:0x1600
	ds_read_b64_tr_b16 v[216:217], v204 offset:0x1e00
	ds_read_b64_tr_b16 v[224:225], v204 offset:0x2600
	ds_read_b64_tr_b16 v[226:227], v204 offset:0x2e00
	ds_read_b64_tr_b16 v[228:229], v204 offset:0x3600
	v_mfma_f32_32x32x16_bf16 v[32:47], v[160:163], v[72:75], v[32:47]
	ds_read_b64_tr_b16 v[230:231], v204 offset:0x3e00
	s_waitcnt lgkmcnt(0)
; #define SBAR() __builtin_amdgcn_sched_barrier(0)
; #define DMA_V(t, buf) do { const char* vb_ = (const char*)Vh + (size_t)(t) * TILEB; \
;         glds16(vb_ + vsrc[0], (unsigned)__builtin_amdgcn_readfirstlane(lds0 + (buf) * SHM_V + widu * 2048)); \
;         glds16(vb_ + vsrc[1], (unsigned)__builtin_amdgcn_readfirstlane(lds0 + (buf) * SHM_V + widu * 2048 + 1024)); } while (0)
; #define WBAR0() do { asm volatile("s_waitcnt vmcnt(0)" ::: "memory"); __syncthreads(); } while (0)
; #define EXPH(P) do { _Pragma("unroll") for (int r = 0; r < 16; ++r) P[r] = __builtin_amdgcn_exp2f(P[r]); } while (0)
;     ...
;         SBAR(); qkt_mix<DQK, NREG>(pA0, pA1, K_lds, qr, qs, r32, hi);
;         finishSM<true>(pB0, pB1, dummy_a, l_reg, pa0, pa1, pa2, pa3); SBAR();
;         pv_d0(o, vb0 + SHM_V, pa0, pa1, pa2, pa3);
;         if (!isY) { EXPH(pA0); }
;         WBAR0();
;     }
;     DMA_V(NT - 1, 1); SBAR();
;     if (isY) { EXPH(pA0); }
;     SBAR(); qkt_mix<DQK, NREG>(pB0, pB1, K_lds + SHM_K, qr, qs, r32, hi);
;     finishSM<true>(pA0, pA1, dummy_a, l_reg, pa0, pa1, pa2, pa3); SBAR();
;     pv_d0(o, vb0, pa0, pa1, pa2, pa3);
	v_mfma_f32_32x32x16_bf16 v[32:47], v[210:213], v[76:79], v[32:47]
	v_mfma_f32_32x32x16_bf16 v[32:47], v[116:119], v[164:167], v[32:47]
	v_mfma_f32_32x32x16_bf16 v[48:63], v[64:67], v[68:71], v[48:63]
	v_exp_f32_e32 v171, v80
	v_exp_f32_e32 v169, v81
	v_exp_f32_e32 v170, v82
	v_exp_f32_e32 v168, v83
	v_add_f32_e32 v80, v184, v200
	v_add_f32_e32 v81, v185, v201
	v_add_f32_e32 v82, v182, v198
	v_add_f32_e32 v83, v183, v199
	v_exp_f32_e32 v167, v84
	v_mfma_f32_32x32x16_bf16 v[64:79], v[156:159], v[108:111], 0
	v_exp_f32_e32 v165, v85
	v_exp_f32_e32 v166, v86
	v_exp_f32_e32 v164, v87
	v_add_f32_e32 v84, v180, v196
	v_add_f32_e32 v85, v181, v197
	v_add_f32_e32 v86, v178, v194
	v_add_f32_e32 v87, v179, v195
	v_mfma_f32_32x32x16_bf16 v[48:63], v[160:163], v[214:217], v[48:63]
	v_exp_f32_e32 v163, v88
	v_exp_f32_e32 v161, v89
	v_exp_f32_e32 v162, v90
	v_exp_f32_e32 v160, v91
	v_add_f32_e32 v88, v176, v192
	v_add_f32_e32 v89, v177, v193
	v_add_f32_e32 v90, v174, v190
	v_add_f32_e32 v91, v175, v191
	v_add_f32_e32 v80, v84, v80
	v_add_f32_e32 v81, v85, v81
	v_mfma_f32_32x32x16_bf16 v[64:79], v[124:127], v[104:107], v[64:79]
	v_add_f32_e64 v82, v86, v82
	v_add_f32_e64 v83, v87, v83
	v_exp_f32_e32 v159, v92
	v_exp_f32_e32 v157, v93
	v_exp_f32_e32 v158, v94
	v_exp_f32_e32 v156, v95
	v_add_f32_e32 v92, v172, v188
	v_add_f32_e32 v93, v173, v189
	v_add_f32_e32 v94, v154, v186
	v_add_f32_e32 v95, v155, v187
	v_mfma_f32_32x32x16_bf16 v[48:63], v[210:213], v[224:227], v[48:63]
	v_add_f32_e64 v80, v88, v80
	v_add_f32_e64 v81, v89, v81
	v_add_f32_e64 v82, v90, v82
	v_add_f32_e64 v83, v91, v83
	s_add_i32 s72, s72, 2
	v_add_f32_e32 v80, v92, v80
	v_add_f32_e32 v81, v93, v81
	v_add_f32_e32 v82, v94, v82
	v_add_f32_e32 v83, v95, v83
	s_waitcnt vmcnt(0)
	s_add_u32 s48, s48, 0xc0000
	v_mfma_f32_32x32x16_bf16 v[64:79], v[120:123], v[100:103], v[64:79]
	v_add_f32_e64 v80, v82, v80
	v_add_f32_e64 v81, v83, v81
	v_add_f32_e32 v124, v134, v141
	s_addc_u32 s49, s49, 0
	v_add_f32_e32 v80, v80, v81
	v_lshl_add_u64 v[152:153], v[152:153], 0, s[28:29]
	s_cmp_gt_u32 s72, 64
	v_add_f32_e32 v134, v124, v80
	v_mfma_f32_32x32x16_bf16 v[48:63], v[116:119], v[228:231], v[48:63]
	s_waitcnt lgkmcnt(0)
	s_barrier
	v_mfma_f32_32x32x16_bf16 v[64:79], v[112:115], v[96:99], v[64:79]
	s_cbranch_scc0 .LBB0_561
	s_cmp_lg_u32 0, -1
	s_cselect_b32 s0, 0, 0
	s_add_i32 s0, s0, s73
	v_lshl_add_u64 v[152:153], v[146:147], 0, s[38:39]
	s_add_i32 s1, s0, 0x4000
	s_mov_b32 s48, m0
	s_mov_b32 m0, s1
	s_nop 0
	global_load_lds_dwordx4 v[152:153], off
	s_mov_b32 m0, s48
	v_lshl_add_u64 v[154:155], v[146:147], 0, s[40:41]
	s_addk_i32 s0, 0x4400
	s_mov_b32 s1, m0
	s_mov_b32 m0, s0
	s_nop 0
	global_load_lds_dwordx4 v[154:155], off
	s_mov_b32 m0, s1
	ds_read_b128 v[80:83], v205 offset:40960
	ds_read_b128 v[124:127], v205 offset:45056
	ds_read_b128 v[112:115], v206 offset:40960
	ds_read_b128 v[120:123], v206 offset:45056
	s_waitcnt lgkmcnt(3)
	v_mfma_f32_32x32x16_bf16 v[80:95], v[80:83], v[108:111], 0
	s_waitcnt lgkmcnt(1)
	v_mfma_f32_32x32x16_bf16 v[80:95], v[112:115], v[104:107], v[80:95]
	ds_read_b128 v[112:115], v207 offset:40960
	ds_read_b128 v[116:119], v207 offset:45056
	s_waitcnt lgkmcnt(1)
	v_mfma_f32_32x32x16_bf16 v[80:95], v[112:115], v[100:103], v[80:95]
	ds_read_b128 v[172:175], v208 offset:40960
	ds_read_b128 v[112:115], v208 offset:45056
	s_waitcnt lgkmcnt(1)
	v_mfma_f32_32x32x16_bf16 v[80:95], v[172:175], v[96:99], v[80:95]
	v_exp_f32_e32 v173, v66
	v_exp_f32_e32 v174, v67
	v_exp_f32_e32 v177, v70
	v_exp_f32_e32 v178, v71
	v_exp_f32_e32 v181, v74
	v_exp_f32_e32 v141, v64
	v_exp_f32_e32 v182, v75
	v_add_f32_e32 v64, v170, v173
	v_exp_f32_e32 v172, v65
	v_exp_f32_e32 v185, v78
	v_add_f32_e32 v64, 0, v64
	v_add_f32_e32 v65, v168, v174
	v_add_f32_e32 v66, v166, v177
	v_exp_f32_e32 v79, v79
	v_add_f32_e32 v65, 0, v65
	v_add_f32_e32 v64, v66, v64
	v_add_f32_e32 v66, v164, v178
	v_add_f32_e32 v65, v66, v65
	v_add_f32_e32 v66, v162, v181
	v_exp_f32_e32 v175, v68
	v_exp_f32_e32 v176, v69
	v_exp_f32_e32 v179, v72
	v_exp_f32_e32 v180, v73
	v_exp_f32_e32 v183, v76
	v_exp_f32_e32 v184, v77
	v_add_f32_e32 v64, v66, v64
	v_add_f32_e32 v66, v160, v182
	v_add_f32_e32 v65, v66, v65
	v_add_f32_e32 v66, v158, v185
	v_add_f32_e32 v64, v66, v64
	v_add_f32_e32 v66, v156, v79
	v_add_f32_e32 v65, v66, v65
	v_add_f32_e32 v186, v171, v141
	v_add_f32_e32 v187, v169, v172
	v_add_f32_e32 v188, v167, v175
	v_add_f32_e32 v189, v165, v176
	v_add_f32_e32 v190, v163, v179
	v_add_f32_e32 v191, v161, v180
	v_add_f32_e32 v192, v159, v183
	v_add_f32_e32 v193, v157, v184
	v_add_f32_e32 v194, v65, v64
	v_cvt_pk_bf16_f32 v64, v171, v169
	v_cvt_pk_bf16_f32 v65, v170, v168
	v_cvt_pk_bf16_f32 v66, v167, v165
	v_cvt_pk_bf16_f32 v67, v166, v164
	v_cvt_pk_bf16_f32 v68, v163, v161
	v_cvt_pk_bf16_f32 v69, v162, v160
	v_cvt_pk_bf16_f32 v70, v159, v157
	v_cvt_pk_bf16_f32 v71, v158, v156
	s_nop 0
	v_permlane32_swap_b32_e32 v64, v66
	v_permlane32_swap_b32_e32 v65, v67
	v_permlane32_swap_b32_e32 v68, v70
	v_cvt_pk_bf16_f32 v72, v141, v172
	v_cvt_pk_bf16_f32 v73, v173, v174
	v_cvt_pk_bf16_f32 v74, v175, v176
	v_cvt_pk_bf16_f32 v75, v177, v178
	v_cvt_pk_bf16_f32 v76, v179, v180
	v_cvt_pk_bf16_f32 v77, v181, v182
	v_cvt_pk_bf16_f32 v78, v183, v184
	v_cvt_pk_bf16_f32 v79, v185, v79
	v_permlane32_swap_b32_e32 v69, v71
	v_permlane32_swap_b32_e32 v72, v74
	v_permlane32_swap_b32_e32 v73, v75
	v_permlane32_swap_b32_e32 v76, v78
	v_permlane32_swap_b32_e32 v77, v79
	ds_read_b64_tr_b16 v[156:157], v203 offset:0
	ds_read_b64_tr_b16 v[158:159], v203 offset:0x800
	ds_read_b64_tr_b16 v[160:161], v203 offset:0x1000
	ds_read_b64_tr_b16 v[162:163], v203 offset:0x1800
	ds_read_b64_tr_b16 v[164:165], v203 offset:0x2000
	ds_read_b64_tr_b16 v[166:167], v203 offset:0x2800
	ds_read_b64_tr_b16 v[168:169], v203 offset:0x3000
	ds_read_b64_tr_b16 v[170:171], v203 offset:0x3800
	s_waitcnt lgkmcnt(0)
; #define SBAR() __builtin_amdgcn_sched_barrier(0)
; #define WBAR0() do { asm volatile("s_waitcnt vmcnt(0)" ::: "memory"); __syncthreads(); } while (0)
; #define EXPH(P) do { _Pragma("unroll") for (int r = 0; r < 16; ++r) P[r] = __builtin_amdgcn_exp2f(P[r]); } while (0)
;     ...
;     pv_d0(o, vb0, pa0, pa1, pa2, pa3);
;     if (!isY) { EXPH(pB0); }
;     WBAR0();
;     if (isY) { EXPH(pB0); }
;     SBAR(); finishSM<true>(pB0, pB1, dummy_a, l_reg, pa0, pa1, pa2, pa3); SBAR();
;     pv_d0(o, vb0 + SHM_V, pa0, pa1, pa2, pa3);
	s_nop 0
	v_mfma_f32_32x32x16_bf16 v[0:15], v[64:67], v[156:159], v[0:15]
	ds_read_b64_tr_b16 v[156:157], v203 offset:0x200
	ds_read_b64_tr_b16 v[158:159], v203 offset:0xa00
	v_mfma_f32_32x32x16_bf16 v[0:15], v[68:71], v[160:163], v[0:15]
	ds_read_b64_tr_b16 v[160:161], v203 offset:0x1200
	ds_read_b64_tr_b16 v[162:163], v203 offset:0x1a00
	v_mfma_f32_32x32x16_bf16 v[0:15], v[72:75], v[164:167], v[0:15]
	ds_read_b64_tr_b16 v[164:165], v203 offset:0x2200
	ds_read_b64_tr_b16 v[166:167], v203 offset:0x2a00
	ds_read_b64_tr_b16 v[172:173], v203 offset:0x3200
	ds_read_b64_tr_b16 v[174:175], v203 offset:0x3a00
	s_waitcnt lgkmcnt(0)
	v_mfma_f32_32x32x16_bf16 v[0:15], v[76:79], v[168:171], v[0:15]
	v_mfma_f32_32x32x16_bf16 v[16:31], v[64:67], v[156:159], v[16:31]
	ds_read_b64_tr_b16 v[156:157], v203 offset:0x400
	ds_read_b64_tr_b16 v[158:159], v203 offset:0xc00
	v_mfma_f32_32x32x16_bf16 v[16:31], v[68:71], v[160:163], v[16:31]
	ds_read_b64_tr_b16 v[160:161], v203 offset:0x1400
	ds_read_b64_tr_b16 v[162:163], v203 offset:0x1c00
	v_mfma_f32_32x32x16_bf16 v[16:31], v[72:75], v[164:167], v[16:31]
	ds_read_b64_tr_b16 v[164:165], v203 offset:0x2400
	ds_read_b64_tr_b16 v[166:167], v203 offset:0x2c00
	ds_read_b64_tr_b16 v[168:169], v203 offset:0x3400
	ds_read_b64_tr_b16 v[170:171], v203 offset:0x3c00
	s_waitcnt lgkmcnt(0)
	v_mfma_f32_32x32x16_bf16 v[16:31], v[76:79], v[172:175], v[16:31]
	v_mfma_f32_32x32x16_bf16 v[32:47], v[64:67], v[156:159], v[32:47]
	ds_read_b64_tr_b16 v[156:157], v203 offset:0x600
	ds_read_b64_tr_b16 v[158:159], v203 offset:0xe00
	v_mfma_f32_32x32x16_bf16 v[32:47], v[68:71], v[160:163], v[32:47]
	ds_read_b64_tr_b16 v[160:161], v203 offset:0x1600
	ds_read_b64_tr_b16 v[162:163], v203 offset:0x1e00
	v_mfma_f32_32x32x16_bf16 v[32:47], v[72:75], v[164:167], v[32:47]
	ds_read_b64_tr_b16 v[164:165], v203 offset:0x2600
	ds_read_b64_tr_b16 v[166:167], v203 offset:0x2e00
	ds_read_b64_tr_b16 v[172:173], v203 offset:0x3600
	ds_read_b64_tr_b16 v[174:175], v203 offset:0x3e00
	s_waitcnt lgkmcnt(0)
	v_mfma_f32_32x32x16_bf16 v[32:47], v[76:79], v[168:171], v[32:47]
	v_mfma_f32_32x32x16_bf16 v[48:63], v[64:67], v[156:159], v[48:63]
	s_waitcnt vmcnt(0)
	v_exp_f32_e32 v80, v80
	v_exp_f32_e32 v81, v81
	v_exp_f32_e32 v82, v82
	v_exp_f32_e32 v83, v83
	v_exp_f32_e32 v84, v84
	v_exp_f32_e32 v85, v85
	v_mfma_f32_32x32x16_bf16 v[48:63], v[68:71], v[160:163], v[48:63]
	v_exp_f32_e32 v86, v86
	v_exp_f32_e32 v87, v87
	v_exp_f32_e32 v88, v88
	v_exp_f32_e32 v89, v89
	v_exp_f32_e32 v90, v90
	v_exp_f32_e32 v91, v91
	v_exp_f32_e32 v92, v92
	v_mfma_f32_32x32x16_bf16 v[48:63], v[72:75], v[164:167], v[48:63]
	v_exp_f32_e32 v93, v93
	v_exp_f32_e32 v94, v94
	v_exp_f32_e32 v95, v95
	s_waitcnt lgkmcnt(0)
	s_barrier
	v_mfma_f32_32x32x16_bf16 v[48:63], v[76:79], v[172:175], v[48:63]
	v_mfma_f32_32x32x16_bf16 v[64:79], v[124:127], v[108:111], 0
	v_mfma_f32_32x32x16_bf16 v[64:79], v[120:123], v[104:107], v[64:79]
	v_add_f32_e32 v104, 0, v186
	v_add_f32_e32 v105, 0, v187
	v_add_f32_e32 v104, v188, v104
	v_add_f32_e32 v105, v189, v105
	v_add_f32_e32 v104, v190, v104
	v_add_f32_e32 v105, v191, v105
	v_add_f32_e32 v104, v192, v104
	v_mfma_f32_32x32x16_bf16 v[64:79], v[116:119], v[100:103], v[64:79]
	v_add_f32_e32 v100, v193, v105
	v_add_f32_e32 v100, v100, v104
	v_add_f32_e32 v100, v194, v100
	v_add_f32_e32 v100, v134, v100
	v_mfma_f32_32x32x16_bf16 v[64:79], v[112:115], v[96:99], v[64:79]
	s_nop 11
	v_exp_f32_e32 v96, v64
	v_exp_f32_e32 v65, v65
	v_exp_f32_e32 v99, v68
	v_exp_f32_e32 v97, v66
	v_exp_f32_e32 v101, v69
	v_exp_f32_e32 v98, v67
	v_exp_f32_e32 v102, v70
	v_exp_f32_e32 v103, v71
	v_add_f32_e32 v64, v80, v96
	v_exp_f32_e32 v104, v72
	v_add_f32_e32 v64, 0, v64
	v_add_f32_e32 v66, v81, v65
	v_add_f32_e32 v69, v84, v99
	v_exp_f32_e32 v105, v73
	v_add_f32_e32 v66, 0, v66
	v_add_f32_e32 v67, v82, v97
	v_add_f32_e32 v64, v69, v64
	v_add_f32_e32 v69, v85, v101
	v_exp_f32_e32 v106, v74
	v_add_f32_e32 v67, 0, v67
	v_add_f32_e32 v68, v83, v98
	v_add_f32_e32 v66, v69, v66
	v_add_f32_e32 v69, v86, v102
	v_exp_f32_e32 v107, v75
	v_add_f32_e32 v68, 0, v68
	v_add_f32_e32 v67, v69, v67
	v_add_f32_e32 v69, v87, v103
	v_exp_f32_e32 v108, v76
	v_add_f32_e32 v68, v69, v68
	v_add_f32_e32 v69, v88, v104
	v_exp_f32_e32 v109, v77
	v_add_f32_e32 v64, v69, v64
	v_add_f32_e32 v69, v89, v105
	v_exp_f32_e32 v110, v78
	v_add_f32_e32 v66, v69, v66
	v_add_f32_e32 v69, v90, v106
	v_exp_f32_e32 v111, v79
	v_add_f32_e32 v67, v69, v67
	v_add_f32_e32 v69, v91, v107
	v_add_f32_e32 v68, v69, v68
	v_add_f32_e32 v69, v92, v108
	v_add_f32_e32 v64, v69, v64
	v_add_f32_e32 v69, v93, v109
	v_add_f32_e32 v66, v69, v66
	v_add_f32_e32 v69, v94, v110
	v_add_f32_e32 v67, v69, v67
	v_add_f32_e32 v69, v95, v111
	v_add_f32_e32 v68, v69, v68
	v_add_f32_e32 v64, v66, v64
	v_add_f32_e32 v66, v68, v67
	v_add_f32_e32 v64, v66, v64
	v_cvt_pk_bf16_f32 v66, v80, v81
	v_cvt_pk_bf16_f32 v67, v82, v83
	v_cvt_pk_bf16_f32 v68, v84, v85
	v_cvt_pk_bf16_f32 v69, v86, v87
	v_add_f32_e32 v64, v100, v64
	v_permlane32_swap_b32_e32 v66, v68
	v_permlane32_swap_b32_e32 v67, v69
	v_cvt_pk_bf16_f32 v70, v88, v89
	v_cvt_pk_bf16_f32 v71, v90, v91
	v_cvt_pk_bf16_f32 v72, v92, v93
	v_cvt_pk_bf16_f32 v73, v94, v95
	v_cvt_pk_bf16_f32 v74, v96, v65
	v_cvt_pk_bf16_f32 v75, v97, v98
	v_cvt_pk_bf16_f32 v76, v99, v101
	v_cvt_pk_bf16_f32 v77, v102, v103
	v_cvt_pk_bf16_f32 v78, v104, v105
	v_cvt_pk_bf16_f32 v79, v106, v107
	v_cvt_pk_bf16_f32 v80, v108, v109
	v_cvt_pk_bf16_f32 v81, v110, v111
	s_nop 0
	v_permlane32_swap_b32_e32 v70, v72
	v_permlane32_swap_b32_e32 v71, v73
	v_permlane32_swap_b32_e32 v74, v76
	v_permlane32_swap_b32_e32 v75, v77
	v_permlane32_swap_b32_e32 v78, v80
	v_permlane32_swap_b32_e32 v79, v81
	ds_read_b64_tr_b16 v[82:83], v204 offset:0
	ds_read_b64_tr_b16 v[84:85], v204 offset:0x800
	ds_read_b64_tr_b16 v[86:87], v204 offset:0x1000
	ds_read_b64_tr_b16 v[88:89], v204 offset:0x1800
	ds_read_b64_tr_b16 v[90:91], v204 offset:0x2000
	ds_read_b64_tr_b16 v[92:93], v204 offset:0x2800
	ds_read_b64_tr_b16 v[94:95], v204 offset:0x3000
	ds_read_b64_tr_b16 v[96:97], v204 offset:0x3800
	s_waitcnt lgkmcnt(0)
; __device__ __forceinline__ unsigned cvt_pk_bf16(float lo, float hi) { unsigned r; asm volatile("v_cvt_pk_bf16_f32 %0, %1, %2" : "=v"(r) : "v"(lo), "v"(hi)); return r; }
; __device__ __forceinline__ int crow(int r, int hi) { return (r & 3) + 8 * (r >> 2) + 4 * hi; }
;     ...
;     pv_d0(o, vb0 + SHM_V, pa0, pa1, pa2, pa3);
;     __builtin_amdgcn_s_setprio(0);
;     (void)dummy_m;
;     { auto rr = __builtin_amdgcn_permlane32_swap(__float_as_uint(l_reg), __float_as_uint(l_reg), false, false); l_reg = __uint_as_float(rr[0]) + __uint_as_float(rr[1]); }
;     {
;         int t2 = threadIdx.x; asm volatile("" : "+v"(t2));
;         const int wid2 = t2 >> 6, lane2 = t2 & 63, r32b = lane2 & 31, hib = lane2 >> 5;
;         float* li2 = (float*)(lds + OFF_WS) + wid2 * 64;
;         if (hib == 0) li2[r32b] = l_reg; asm volatile("s_waitcnt lgkmcnt(0)" ::: "memory");
;         __syncthreads();
;         bf16_t* stash = (bf16_t*)(lds + OFF_Q) + wid2 * 4096;
;         bf16_t* stg = (mode == 1) ? stash : ((bf16_t*)lds + wid2 * 4096);
; #pragma unroll
;         for (int r = 0; r < 16; ++r) { const int orow = crow(r, hib); const float rl = __builtin_amdgcn_rcpf(li2[orow]);
; #pragma unroll
;             for (int d0 = 0; d0 < 4; ++d0) { const float v = o[d0][r] * rl; stg[orow * 128 + d0 * 32 + r32b] = (bf16_t)(cvt_pk_bf16(v, v) & 0xffffu); } }
	s_nop 0
	v_mfma_f32_32x32x16_bf16 v[0:15], v[66:69], v[82:85], v[0:15]
	ds_read_b64_tr_b16 v[82:83], v204 offset:0x200
	ds_read_b64_tr_b16 v[84:85], v204 offset:0xa00
	v_mfma_f32_32x32x16_bf16 v[0:15], v[70:73], v[86:89], v[0:15]
	ds_read_b64_tr_b16 v[86:87], v204 offset:0x1200
	ds_read_b64_tr_b16 v[88:89], v204 offset:0x1a00
	v_mfma_f32_32x32x16_bf16 v[0:15], v[74:77], v[90:93], v[0:15]
	ds_read_b64_tr_b16 v[90:91], v204 offset:0x2200
	ds_read_b64_tr_b16 v[92:93], v204 offset:0x2a00
	ds_read_b64_tr_b16 v[98:99], v204 offset:0x3200
	ds_read_b64_tr_b16 v[100:101], v204 offset:0x3a00
	s_waitcnt lgkmcnt(0)
	v_mfma_f32_32x32x16_bf16 v[0:15], v[78:81], v[94:97], v[0:15]
	v_mfma_f32_32x32x16_bf16 v[16:31], v[66:69], v[82:85], v[16:31]
	ds_read_b64_tr_b16 v[82:83], v204 offset:0x400
	ds_read_b64_tr_b16 v[84:85], v204 offset:0xc00
	v_mfma_f32_32x32x16_bf16 v[16:31], v[70:73], v[86:89], v[16:31]
	ds_read_b64_tr_b16 v[86:87], v204 offset:0x1400
	ds_read_b64_tr_b16 v[88:89], v204 offset:0x1c00
	v_mfma_f32_32x32x16_bf16 v[16:31], v[74:77], v[90:93], v[16:31]
	ds_read_b64_tr_b16 v[90:91], v204 offset:0x2400
	ds_read_b64_tr_b16 v[92:93], v204 offset:0x2c00
	ds_read_b64_tr_b16 v[94:95], v204 offset:0x3400
	ds_read_b64_tr_b16 v[96:97], v204 offset:0x3c00
	s_waitcnt lgkmcnt(0)
	v_mfma_f32_32x32x16_bf16 v[16:31], v[78:81], v[98:101], v[16:31]
	v_mfma_f32_32x32x16_bf16 v[32:47], v[66:69], v[82:85], v[32:47]
	ds_read_b64_tr_b16 v[82:83], v204 offset:0x600
	ds_read_b64_tr_b16 v[84:85], v204 offset:0xe00
	v_mfma_f32_32x32x16_bf16 v[32:47], v[70:73], v[86:89], v[32:47]
	ds_read_b64_tr_b16 v[86:87], v204 offset:0x1600
	ds_read_b64_tr_b16 v[88:89], v204 offset:0x1e00
	v_mfma_f32_32x32x16_bf16 v[32:47], v[74:77], v[90:93], v[32:47]
	ds_read_b64_tr_b16 v[90:91], v204 offset:0x2600
	ds_read_b64_tr_b16 v[92:93], v204 offset:0x2e00
	ds_read_b64_tr_b16 v[98:99], v204 offset:0x3600
	ds_read_b64_tr_b16 v[100:101], v204 offset:0x3e00
	s_waitcnt lgkmcnt(0)
	v_mfma_f32_32x32x16_bf16 v[32:47], v[78:81], v[94:97], v[32:47]
	v_mfma_f32_32x32x16_bf16 v[48:63], v[66:69], v[82:85], v[48:63]
	v_mfma_f32_32x32x16_bf16 v[48:63], v[70:73], v[86:89], v[48:63]
	v_mfma_f32_32x32x16_bf16 v[48:63], v[74:77], v[90:93], v[48:63]
	v_mfma_f32_32x32x16_bf16 v[48:63], v[78:81], v[98:101], v[48:63]
	s_setprio 0
	v_mov_b32_e32 v66, v218
	v_mov_b32_e32 v68, v64
	s_nop 1
	v_permlane32_swap_b32_e32 v64, v68
	v_and_b32_e32 v69, 32, v66
	v_and_b32_e32 v67, 0x3fffffc0, v66
	v_and_b32_e32 v65, 31, v66
	v_lshl_add_u32 v67, v67, 2, s35
	v_cmp_eq_u32_e32 vcc, 0, v69
	s_and_saveexec_b64 s[0:1], vcc
	v_add_f32_e32 v64, v64, v68
	v_lshl_add_u32 v68, v65, 2, v67
	ds_write_b32 v68, v64
	s_or_b64 exec, exec, s[0:1]
	v_lshrrev_b32_e32 v64, 3, v66
	v_and_b32_e32 v64, 4, v64
	v_lshl_add_u32 v67, v64, 2, v67
	s_waitcnt lgkmcnt(0)
	s_waitcnt lgkmcnt(0)
	s_barrier
	ds_read_b32 v68, v67
	v_lshlrev_b32_e32 v66, 7, v66
	v_and_b32_e32 v66, 0xffffe000, v66
	s_add_i32 s48, 0, 0x10800
	v_add_u32_e32 v66, s48, v66
	s_waitcnt lgkmcnt(0)
	v_rcp_f32_e32 v68, v68
	v_lshlrev_b32_e32 v65, 1, v65
	v_lshlrev_b32_e32 v64, 8, v64
	v_add3_u32 v64, v66, v65, v64
	v_mul_f32_e32 v0, v0, v68
	v_cvt_pk_bf16_f32 v0, v0, v0
	ds_write_b16 v64, v0
	v_mul_f32_e32 v0, v16, v68
	v_cvt_pk_bf16_f32 v0, v0, v0
	ds_write_b16 v64, v0 offset:64
	v_mul_f32_e32 v0, v32, v68
	v_cvt_pk_bf16_f32 v0, v0, v0
	ds_write_b16 v64, v0 offset:128
	v_mul_f32_e32 v0, v48, v68
	v_cvt_pk_bf16_f32 v0, v0, v0
	ds_read_b32 v16, v67 offset:4
	ds_write_b16 v64, v0 offset:192
	v_readfirstlane_b32 s49, v202
	s_lshl_b32 s55, s49, 10
	s_cmp_lg_u32 0, -1
	s_waitcnt lgkmcnt(1)
	v_rcp_f32_e32 v16, v16
	s_cselect_b32 s0, 0, 0
	s_add_i32 s0, s0, s55
	s_add_i32 s0, s0, 0x8000
	v_mul_f32_e32 v0, v1, v16
	v_cvt_pk_bf16_f32 v0, v0, v0
	ds_write_b16 v64, v0 offset:256
	v_mul_f32_e32 v0, v17, v16
	v_cvt_pk_bf16_f32 v0, v0, v0
	ds_write_b16 v64, v0 offset:320
	v_mul_f32_e32 v0, v33, v16
	v_cvt_pk_bf16_f32 v0, v0, v0
	ds_write_b16 v64, v0 offset:384
	v_mul_f32_e32 v0, v49, v16
	v_cvt_pk_bf16_f32 v0, v0, v0
	ds_read_b32 v1, v67 offset:8
	ds_write_b16 v64, v0 offset:448
	s_waitcnt lgkmcnt(1)
	v_rcp_f32_e32 v1, v1
	s_nop 0
	v_mul_f32_e32 v0, v2, v1
	v_cvt_pk_bf16_f32 v0, v0, v0
	ds_write_b16 v64, v0 offset:512
	v_mul_f32_e32 v0, v18, v1
	v_cvt_pk_bf16_f32 v0, v0, v0
	ds_write_b16 v64, v0 offset:576
	v_mul_f32_e32 v0, v34, v1
	v_cvt_pk_bf16_f32 v0, v0, v0
	ds_write_b16 v64, v0 offset:640
	v_mul_f32_e32 v0, v50, v1
	v_cvt_pk_bf16_f32 v0, v0, v0
	ds_read_b32 v1, v67 offset:12
	ds_write_b16 v64, v0 offset:704
	s_waitcnt lgkmcnt(1)
	v_rcp_f32_e32 v1, v1
	s_nop 0
	v_mul_f32_e32 v0, v3, v1
	v_cvt_pk_bf16_f32 v0, v0, v0
	ds_write_b16 v64, v0 offset:768
	v_mul_f32_e32 v0, v19, v1
	v_cvt_pk_bf16_f32 v0, v0, v0
	ds_write_b16 v64, v0 offset:832
	v_mul_f32_e32 v0, v35, v1
	v_cvt_pk_bf16_f32 v0, v0, v0
	ds_write_b16 v64, v0 offset:896
	v_mul_f32_e32 v0, v51, v1
	v_cvt_pk_bf16_f32 v0, v0, v0
	ds_read_b32 v1, v67 offset:32
	ds_write_b16 v64, v0 offset:960
	s_waitcnt lgkmcnt(1)
	v_rcp_f32_e32 v1, v1
	s_nop 0
	v_mul_f32_e32 v0, v4, v1
	v_cvt_pk_bf16_f32 v0, v0, v0
	ds_write_b16 v64, v0 offset:2048
	v_mul_f32_e32 v0, v20, v1
	v_cvt_pk_bf16_f32 v0, v0, v0
	ds_write_b16 v64, v0 offset:2112
	v_mul_f32_e32 v0, v36, v1
	v_cvt_pk_bf16_f32 v0, v0, v0
	ds_write_b16 v64, v0 offset:2176
	v_mul_f32_e32 v0, v52, v1
	v_cvt_pk_bf16_f32 v0, v0, v0
	ds_read_b32 v1, v67 offset:36
	ds_write_b16 v64, v0 offset:2240
	s_waitcnt lgkmcnt(1)
; __device__ __forceinline__ int crow(int r, int hi) { return (r & 3) + 8 * (r >> 2) + 4 * hi; }
;     ...
;         const bf16_t* Qw = Qb + (size_t)(wid * QBLK + r32) * LDQ + hi * 8;
; #pragma unroll
;         for (int d0 = 0; d0 < NREG; ++d0) qr[d0] = *(const bf16x8*)(Qw + d0 * 16);
; #pragma unroll
;         for (int d0 = NREG; d0 < ND0; ++d0) *(bf16x8*)(qs + (d0 - NREG) * 1024) = *(const bf16x8*)(Qw + d0 * 16);
;     }
;     const int widu = __builtin_amdgcn_readfirstlane(wid);
;     const int vb0 = (int)(uintptr_t)V_lds + v_rd_base(lane);
;     unsigned ksrc[2], vsrc[2];
; #pragma unroll
;     for (int i = 0; i < 2; ++i) {
;         if (DQK == 128) { const int j = wid * 2 + i, row = 4 * j + (lane >> 4), c = (lane & 15) ^ (row & 15); ksrc[i] = (unsigned)(row * LDK + c * 8) * 2u; }
;     ...
; #pragma unroll
;         for (int r = 0; r < 16; ++r) { const int orow = crow(r, hib); const float rl = __builtin_amdgcn_rcpf(li2[orow]);
; #pragma unroll
;             for (int d0 = 0; d0 < 4; ++d0) { const float v = o[d0][r] * rl; stg[orow * 128 + d0 * 32 + r32b] = (bf16_t)(cvt_pk_bf16(v, v) & 0xffffu); } }
;         asm volatile("s_waitcnt lgkmcnt(0)" ::: "memory");
;         if (mode != 1) {
;             bf16_t* Ow = Ob + (size_t)(wid2 * QBLK) * LDO;
;             const int ch = lane2 & 15;
;             float gg[8];
;             if (mode == 2) {
; #pragma unroll
;                 for (int e = 0; e < 8; ++e) gg[e] = sg[ch * 8 + e] * 0.8f; }
; #pragma unroll
;             for (int i = 0; i < 8; ++i) { const int row = i * 4 + (lane2 >> 4); u32x4 v = *(const u32x4*)(stg + row * 128 + ch * 8);
;                 if (mode == 2) { const u32x4 v0 = *(const u32x4*)(stash + row * 128 + ch * 8); float x0[8], x1[8]; unpack8(v0, x0); unpack8(v, x1); float ss = 0.f;
; #pragma unroll
;                     for (int e = 0; e < 8; ++e) { x0[e] = x0[e] - lam * x1[e]; ss += x0[e] * x0[e]; }
;                     ss += __shfl_xor(ss, 1); ss += __shfl_xor(ss, 2); ss += __shfl_xor(ss, 4); ss += __shfl_xor(ss, 8);
;                     const float rstd = rsqrtf(ss * (1.0f / 128) + EPS);
; #pragma unroll
;                     for (int e = 0; e < 8; ++e) x0[e] = x0[e] * rstd * gg[e];
;                     v = pack8(x0); }
;                 *(u32x4*)(Ow + (size_t)row * LDO + ch * 8) = v; }
;         }
;     }
;     asm volatile("s_waitcnt vmcnt(0)" ::: "memory");
;     __syncthreads();
	v_rcp_f32_e32 v1, v1
	s_nop 0
	v_mul_f32_e32 v0, v5, v1
	v_cvt_pk_bf16_f32 v0, v0, v0
	ds_write_b16 v64, v0 offset:2304
	v_mul_f32_e32 v0, v21, v1
	v_cvt_pk_bf16_f32 v0, v0, v0
	ds_write_b16 v64, v0 offset:2368
	v_mul_f32_e32 v0, v37, v1
	v_cvt_pk_bf16_f32 v0, v0, v0
	ds_write_b16 v64, v0 offset:2432
	v_mul_f32_e32 v0, v53, v1
	v_cvt_pk_bf16_f32 v0, v0, v0
	ds_read_b32 v1, v67 offset:40
	ds_write_b16 v64, v0 offset:2496
	s_waitcnt lgkmcnt(1)
	v_rcp_f32_e32 v1, v1
	s_nop 0
	v_mul_f32_e32 v0, v6, v1
	v_cvt_pk_bf16_f32 v0, v0, v0
	ds_write_b16 v64, v0 offset:2560
	v_mul_f32_e32 v0, v22, v1
	v_cvt_pk_bf16_f32 v0, v0, v0
	ds_write_b16 v64, v0 offset:2624
	v_mul_f32_e32 v0, v38, v1
	v_cvt_pk_bf16_f32 v0, v0, v0
	ds_write_b16 v64, v0 offset:2688
	v_mul_f32_e32 v0, v54, v1
	v_cvt_pk_bf16_f32 v0, v0, v0
	ds_read_b32 v1, v67 offset:44
	ds_write_b16 v64, v0 offset:2752
	s_waitcnt lgkmcnt(1)
	v_rcp_f32_e32 v1, v1
	s_nop 0
	v_mul_f32_e32 v0, v7, v1
	v_cvt_pk_bf16_f32 v0, v0, v0
	ds_write_b16 v64, v0 offset:2816
	v_mul_f32_e32 v0, v23, v1
	v_cvt_pk_bf16_f32 v0, v0, v0
	ds_write_b16 v64, v0 offset:2880
	v_mul_f32_e32 v0, v39, v1
	v_cvt_pk_bf16_f32 v0, v0, v0
	ds_write_b16 v64, v0 offset:2944
	v_mul_f32_e32 v0, v55, v1
	v_cvt_pk_bf16_f32 v0, v0, v0
	ds_read_b32 v1, v67 offset:64
	ds_write_b16 v64, v0 offset:3008
	s_waitcnt lgkmcnt(1)
	v_rcp_f32_e32 v1, v1
	s_nop 0
	v_mul_f32_e32 v0, v8, v1
	v_cvt_pk_bf16_f32 v0, v0, v0
	ds_write_b16 v64, v0 offset:4096
	v_mul_f32_e32 v0, v24, v1
	v_cvt_pk_bf16_f32 v0, v0, v0
	ds_write_b16 v64, v0 offset:4160
	v_mul_f32_e32 v0, v40, v1
	v_cvt_pk_bf16_f32 v0, v0, v0
	ds_write_b16 v64, v0 offset:4224
	v_mul_f32_e32 v0, v56, v1
	v_cvt_pk_bf16_f32 v0, v0, v0
	ds_read_b32 v1, v67 offset:68
	ds_write_b16 v64, v0 offset:4288
	s_waitcnt lgkmcnt(1)
	v_rcp_f32_e32 v1, v1
	s_nop 0
	v_mul_f32_e32 v0, v9, v1
	v_cvt_pk_bf16_f32 v0, v0, v0
	ds_write_b16 v64, v0 offset:4352
	v_mul_f32_e32 v0, v25, v1
	v_cvt_pk_bf16_f32 v0, v0, v0
	ds_write_b16 v64, v0 offset:4416
	v_mul_f32_e32 v0, v41, v1
	v_cvt_pk_bf16_f32 v0, v0, v0
	ds_write_b16 v64, v0 offset:4480
	v_mul_f32_e32 v0, v57, v1
	v_cvt_pk_bf16_f32 v0, v0, v0
	ds_read_b32 v1, v67 offset:72
	ds_write_b16 v64, v0 offset:4544
	s_waitcnt lgkmcnt(1)
	v_rcp_f32_e32 v1, v1
	s_nop 0
	v_mul_f32_e32 v0, v10, v1
	v_cvt_pk_bf16_f32 v0, v0, v0
	ds_write_b16 v64, v0 offset:4608
	v_mul_f32_e32 v0, v26, v1
	v_cvt_pk_bf16_f32 v0, v0, v0
	ds_write_b16 v64, v0 offset:4672
	v_mul_f32_e32 v0, v42, v1
	v_cvt_pk_bf16_f32 v0, v0, v0
	ds_write_b16 v64, v0 offset:4736
	v_mul_f32_e32 v0, v58, v1
	v_cvt_pk_bf16_f32 v0, v0, v0
	ds_read_b32 v1, v67 offset:76
	ds_write_b16 v64, v0 offset:4800
	s_waitcnt lgkmcnt(1)
	v_rcp_f32_e32 v1, v1
	s_nop 0
	v_mul_f32_e32 v0, v11, v1
	v_cvt_pk_bf16_f32 v0, v0, v0
	ds_write_b16 v64, v0 offset:4864
	v_mul_f32_e32 v0, v27, v1
	v_cvt_pk_bf16_f32 v0, v0, v0
	ds_write_b16 v64, v0 offset:4928
	v_mul_f32_e32 v0, v43, v1
	v_cvt_pk_bf16_f32 v0, v0, v0
	ds_write_b16 v64, v0 offset:4992
	v_mul_f32_e32 v0, v59, v1
	v_cvt_pk_bf16_f32 v0, v0, v0
	ds_read_b32 v1, v67 offset:96
	ds_write_b16 v64, v0 offset:5056
	s_waitcnt lgkmcnt(1)
	v_rcp_f32_e32 v1, v1
	s_nop 0
	v_mul_f32_e32 v0, v12, v1
	v_cvt_pk_bf16_f32 v0, v0, v0
	ds_write_b16 v64, v0 offset:6144
	v_mul_f32_e32 v0, v28, v1
	v_cvt_pk_bf16_f32 v0, v0, v0
	ds_write_b16 v64, v0 offset:6208
	v_mul_f32_e32 v0, v44, v1
	v_cvt_pk_bf16_f32 v0, v0, v0
	ds_write_b16 v64, v0 offset:6272
	v_mul_f32_e32 v0, v60, v1
	v_cvt_pk_bf16_f32 v0, v0, v0
	ds_read_b32 v1, v67 offset:100
	ds_write_b16 v64, v0 offset:6336
	s_waitcnt lgkmcnt(1)
	v_rcp_f32_e32 v1, v1
	s_nop 0
	v_mul_f32_e32 v0, v13, v1
	v_cvt_pk_bf16_f32 v0, v0, v0
	ds_write_b16 v64, v0 offset:6400
	v_mul_f32_e32 v0, v29, v1
	v_cvt_pk_bf16_f32 v0, v0, v0
	ds_write_b16 v64, v0 offset:6464
	v_mul_f32_e32 v0, v45, v1
	v_cvt_pk_bf16_f32 v0, v0, v0
	ds_write_b16 v64, v0 offset:6528
	v_mul_f32_e32 v0, v61, v1
	v_cvt_pk_bf16_f32 v0, v0, v0
	ds_read_b32 v1, v67 offset:104
	ds_write_b16 v64, v0 offset:6592
	s_waitcnt lgkmcnt(1)
	v_rcp_f32_e32 v1, v1
	s_nop 0
	v_mul_f32_e32 v0, v14, v1
	v_cvt_pk_bf16_f32 v0, v0, v0
	ds_write_b16 v64, v0 offset:6656
	v_mul_f32_e32 v0, v30, v1
	v_cvt_pk_bf16_f32 v0, v0, v0
	ds_write_b16 v64, v0 offset:6720
	v_mul_f32_e32 v0, v46, v1
	v_cvt_pk_bf16_f32 v0, v0, v0
	ds_write_b16 v64, v0 offset:6784
	v_mul_f32_e32 v0, v62, v1
	v_cvt_pk_bf16_f32 v0, v0, v0
	ds_read_b32 v1, v67 offset:108
	ds_write_b16 v64, v0 offset:6848
	s_waitcnt lgkmcnt(1)
	v_rcp_f32_e32 v1, v1
	s_nop 0
	v_mul_f32_e32 v0, v15, v1
	v_cvt_pk_bf16_f32 v0, v0, v0
	ds_write_b16 v64, v0 offset:6912
	v_mul_f32_e32 v0, v31, v1
	v_cvt_pk_bf16_f32 v0, v0, v0
	ds_write_b16 v64, v0 offset:6976
	v_mul_f32_e32 v0, v47, v1
	v_cvt_pk_bf16_f32 v0, v0, v0
	ds_write_b16 v64, v0 offset:7040
	v_mul_f32_e32 v0, v63, v1
	v_cvt_pk_bf16_f32 v0, v0, v0
	ds_write_b16 v64, v0 offset:7104
	s_waitcnt lgkmcnt(0)
	s_waitcnt vmcnt(0)
	s_waitcnt lgkmcnt(0)
	s_barrier
	global_load_dwordx4 v[108:111], v[144:145], off offset:128
	global_load_dwordx4 v[104:107], v[144:145], off offset:160
	global_load_dwordx4 v[100:103], v[144:145], off offset:192
	global_load_dwordx4 v[96:99], v[144:145], off offset:224
	v_lshl_add_u64 v[0:1], v[150:151], 0, s[42:43]
	s_mov_b32 s1, m0
	s_mov_b32 m0, s0
	s_nop 0
	global_load_lds_dwordx4 v[0:1], off
	s_mov_b32 m0, s1
	s_waitcnt vmcnt(0)
	s_nop 0
	v_readfirstlane_b32 s1, v218
	s_cmpk_lt_i32 s1, 0x100
	s_barrier
	s_cbranch_scc1 .LBB0_566
	s_setprio 0
